# compressed branch: constant-bias fast variant for tiles entirely >= 790 tokens back (inside the tile loop); plus phase-4 loop order split
# baseline (speedup 1.0000x reference)
; __device__ __forceinline__ float bf2f(bf16_t v) { return __uint_as_float(((unsigned)v) << 16); }
; __device__ __forceinline__ float sigmoidf_(float x) { return __builtin_amdgcn_rcpf(1.0f + __expf(-x)); }
; __device__ __forceinline__ void nsa_unit(LAS unsigned char* lds, const Ctx& P, int l, int b, int hkv, int tb) {
;     ...
;         const int ntile = ((t0 >> 4) + 2) / 64 + 1;
;         const int tqs = t0 + 32 * th + 16 * sb + c;
;         bf16x8 qs[2];
; #pragma unroll
;         for (int ks = 0; ks < 2; ++ks) qs[ks] = load_q_scaled(H + ((size_t)b * SEQ + tqs) * LDH + C_Q + hq * 64 + ks * 32 + 8 * i, 0.125f);
; #pragma unroll
;         for (int pr = 0; pr < 2; ++pr) if (2 * pr < ntile) {
;             const bool hasb = 2 * pr + 1 < ntile;
;             __syncthreads();
;             load2(KC, VC, 64, 128 * pr, 128 * pr + 64, hasb, 255);
;     ...
;         const float g0 = sigmoidf_(bf2f(H[((size_t)b * SEQ + tqs) * LDH + C_GL + hq]) + P.in[21][l * 48 + hq]) * inv;
.LBB0_203:
	v_mov_b32_e32 v65, s74
	ds_read_b64 v[66:67], v65
	ds_read_b32 v165, v131 offset:3160
	s_mov_b64 s[24:25], -1
	v_lshlrev_b32_e32 v86, 1, v96
	v_add_u32_e32 v86, 0x5400, v86
	v_add_co_u32_e32 v62, vcc, v86, v128
	s_nop 1
	v_addc_co_u32_e32 v63, vcc, 0, v129, vcc
	global_load_ushort v108, v[62:63], off
	v_lshlrev_b32_e32 v86, 1, v96
	v_add_u32_e32 v86, 0x5400, v86
	v_add_co_u32_e32 v62, vcc, v86, v122
	s_nop 1
	v_addc_co_u32_e32 v63, vcc, 0, v123, vcc
	global_load_ushort v109, v[62:63], off
	s_lshr_b32 s26, s55, 4
	s_add_u32 s26, s26, 2
	s_lshr_b32 s26, s26, 6
	s_add_u32 s26, s26, 1
	s_lshl_b32 s44, s61, 2
	s_or_b32 s44, s44, s60
	s_lshl_b32 s44, s44, 15
	s_add_u32 s44, s44, 0x33203000
	s_add_u32 s20, s68, s44
	s_addc_u32 s21, s69, 0
	v_lshlrev_b32_e32 v139, 4, v234
	v_mov_b32_e32 v86, v139
	v_add_u32_e32 v87, 0x80000, v86
	global_load_dwordx4 v[198:201], v86, s[20:21]
	global_load_dwordx4 v[202:205], v87, s[20:21]
	s_cmp_lt_u32 s26, 2
	s_cbranch_scc1 .Lcm_ld_1
	v_add_u32_e32 v86, 0x2000, v139
	v_add_u32_e32 v87, 0x80000, v86
	global_load_dwordx4 v[206:209], v86, s[20:21]
	global_load_dwordx4 v[210:213], v87, s[20:21]
	s_cmp_lt_u32 s26, 3
	s_cbranch_scc1 .Lcm_ld_1
	v_add_u32_e32 v86, 0x4000, v139
	v_add_u32_e32 v87, 0x80000, v86
	global_load_dwordx4 v[214:217], v86, s[20:21]
	global_load_dwordx4 v[218:221], v87, s[20:21]
	s_cmp_lt_u32 s26, 4
	s_cbranch_scc1 .Lcm_ld_1
	v_add_u32_e32 v86, 0x6000, v139
	v_add_u32_e32 v87, 0x80000, v86
	global_load_dwordx4 v[222:225], v86, s[20:21]
	global_load_dwordx4 v[226:229], v87, s[20:21]

; template <int D, class SF>
; __device__ __forceinline__ void attn_step(const bf16x8 (&qf)[D / 32], const LAS bf16_t* Ks, const LAS bf16_t* Vt, f32x4 (&o)[D / 16], float& m, float& lsum, float& alpha_out, bf16x8& pf0_out, bf16x8& pf1_out, const int lane, SF sf) {
;     ...
;     for (int ks = 0; ks < D / 32; ++ks) {
; #pragma unroll
;         for (int t = 0; t < 4; ++t) { const bf16x8 kf = *(const LAS bf16x8*)(Ks + (16 * t + c) * KSTR + ks * 32 + 8 * i); s[t] = mfma16(kf, qf[ks], s[t]); }
;     }
;     float v[16];
; #pragma unroll
;     for (int t = 0; t < 4; ++t)
; #pragma unroll
;         for (int r = 0; r < 4; ++r) v[4 * t + r] = sf(16 * t + 4 * i + r, s[t][r]);
;     float mx = fmaxf(fmaxf(fmaxf(v[0], v[1]), fmaxf(v[2], v[3])), fmaxf(fmaxf(v[4], v[5]), fmaxf(v[6], v[7])));
;     mx = fmaxf(mx, fmaxf(fmaxf(fmaxf(v[8], v[9]), fmaxf(v[10], v[11])), fmaxf(fmaxf(v[12], v[13]), fmaxf(v[14], v[15]))));
;     mx = rows_max(mx);
;     const float mnew = fmaxf(m, mx);
;     const float mc = fmaxf(mnew, -1e20f);
;     const float alpha = __builtin_amdgcn_exp2f(fmaxf(m, -1e20f) - mc);
;     float p[16], rs = 0.f;
; #pragma unroll
;     for (int r = 0; r < 16; ++r) { p[r] = __builtin_amdgcn_exp2f(v[r] - mc); rs += p[r]; }
;     rs = rows_sum(rs);
;     lsum = lsum * alpha + rs; m = mnew;
;     union { u32x4 u; bf16x8 b; } pk0, pk1;
;     pk0.u.x = cvt_pk_bf16(p[0], p[1]); pk0.u.y = cvt_pk_bf16(p[2], p[3]); pk0.u.z = cvt_pk_bf16(p[4], p[5]); pk0.u.w = cvt_pk_bf16(p[6], p[7]);
;     pk1.u.x = cvt_pk_bf16(p[8], p[9]); pk1.u.y = cvt_pk_bf16(p[10], p[11]); pk1.u.z = cvt_pk_bf16(p[12], p[13]); pk1.u.w = cvt_pk_bf16(p[14], p[15]);
; __device__ __forceinline__ void nsa_unit(LAS unsigned char* lds, const Ctx& P, int l, int b, int hkv, int tb) {
;     ...
;             for (int sl = 0; sl < 2; ++sl) if (sl == 0 || hasb) {
;                 const int kt = 2 * pr + sl; const LAS bf16_t* Ks = KV + sl * 9216; const LAS bf16_t* Vt = Ks + 4608; const int nb = kt * 64;
;                 attn_step<64>(qs, Ks, Vt, o, m, lsum, alpha, pf, pf1, lane,
;                     [&](int kk, float s) { const int dist = tqs - (16 * (nb + kk) + 31); return dist >= 0 ? s * LOG2E + lut[min((unsigned)dist, 1023u)] : NEGBIG; });
; #pragma unroll
;                 for (int jt = 0; jt < 4; ++jt) oi[jt] *= alpha;
;                 oi[kt] = mfma16(ovA[0], pf, oi[kt]); oi[kt] = mfma16(ovA[1], pf1, oi[kt]);
.Lcm_top_3:
	s_sub_i32 s44, s55, s5
	s_cmp_ge_i32 s44, 0x706
	s_cbranch_scc0 .Lcm_gen_4
	ds_read_b128 v[198:201], v192 offset:16384
	ds_read_b128 v[206:209], v192 offset:18944
	ds_read_b128 v[202:205], v192 offset:16448
	ds_read_b128 v[210:213], v192 offset:19008
	ds_read_b128 v[214:217], v192 offset:21504
	ds_read_b128 v[222:225], v192 offset:24064
	ds_read_b128 v[218:221], v192 offset:21568
	ds_read_b128 v[226:229], v192 offset:24128
	s_waitcnt lgkmcnt(6)
	v_mfma_f32_16x16x32_bf16 v[62:65], v[198:201], v[2:5], 0
	v_mfma_f32_16x16x32_bf16 v[66:69], v[206:209], v[2:5], 0
	s_waitcnt lgkmcnt(4)
	v_mfma_f32_16x16x32_bf16 v[62:65], v[202:205], v[6:9], v[62:65]
	v_mfma_f32_16x16x32_bf16 v[66:69], v[210:213], v[6:9], v[66:69]
	s_waitcnt lgkmcnt(2)
	v_mfma_f32_16x16x32_bf16 v[70:73], v[214:217], v[2:5], 0
	v_mfma_f32_16x16x32_bf16 v[74:77], v[222:225], v[2:5], 0
	s_waitcnt lgkmcnt(0)
	v_mfma_f32_16x16x32_bf16 v[70:73], v[218:221], v[6:9], v[70:73]
	v_mfma_f32_16x16x32_bf16 v[74:77], v[226:229], v[6:9], v[74:77]
	ds_read_b64_tr_b16 v[198:199], v193 offset:26624
	ds_read_b64_tr_b16 v[200:201], v193 offset:29184
	ds_read_b64_tr_b16 v[202:203], v193 offset:31744
	ds_read_b64_tr_b16 v[204:205], v193 offset:34304
	ds_read_b64_tr_b16 v[206:207], v193 offset:26656
	ds_read_b64_tr_b16 v[208:209], v193 offset:29216
	ds_read_b64_tr_b16 v[210:211], v193 offset:31776
	ds_read_b64_tr_b16 v[212:213], v193 offset:34336
	ds_read_b64_tr_b16 v[214:215], v193 offset:26688
	ds_read_b64_tr_b16 v[216:217], v193 offset:29248
	ds_read_b64_tr_b16 v[218:219], v193 offset:31808
	ds_read_b64_tr_b16 v[220:221], v193 offset:34368
	ds_read_b64_tr_b16 v[222:223], v193 offset:26720
	ds_read_b64_tr_b16 v[224:225], v193 offset:29280
	ds_read_b64_tr_b16 v[226:227], v193 offset:31840
	ds_read_b64_tr_b16 v[228:229], v193 offset:34400
	v_max3_f32 v86, v62, v63, v64
	v_max3_f32 v87, v65, v66, v67
	v_max3_f32 v88, v68, v69, v70
	v_max3_f32 v89, v71, v72, v73
	v_max3_f32 v91, v74, v75, v76
	v_max3_f32 v86, v86, v87, v77
	v_max3_f32 v88, v88, v89, v91
	v_max_f32_e32 v86, v86, v88
	v_mov_b32_e32 v87, v86
	s_nop 1
	v_permlane16_swap_b32_e32 v86, v87
	v_max_f32_e32 v86, v86, v87
	v_mov_b32_e32 v87, v86
	s_nop 1
	v_permlane32_swap_b32_e32 v86, v87
	v_max_f32_e32 v86, v86, v87
	v_fmamk_f32 v86, v86, 0x3fb8aa3b, v165
	v_cndmask_b32_e64 v86, v243, v86, s[24:25]
	v_max_f32_e32 v88, v137, v86
	v_max_f32_e32 v90, 0xe0ad78ec, v137
	v_max_f32_e32 v89, 0xe0ad78ec, v88
	v_sub_f32_e32 v90, v90, v89
	v_mov_b32_e32 v137, v88
	v_exp_f32_e32 v90, v90
	v_sub_f32_e32 v91, v165, v89
	v_cndmask_b32_e64 v91, v243, v91, s[24:25]
	v_fmamk_f32 v62, v62, 0x3fb8aa3b, v91
	v_fmamk_f32 v63, v63, 0x3fb8aa3b, v91
	v_fmamk_f32 v64, v64, 0x3fb8aa3b, v91
	v_fmamk_f32 v65, v65, 0x3fb8aa3b, v91
	v_exp_f32_e32 v62, v62
	v_exp_f32_e32 v63, v63
	v_exp_f32_e32 v64, v64
	v_exp_f32_e32 v65, v65
	v_fmamk_f32 v66, v66, 0x3fb8aa3b, v91
	v_fmamk_f32 v67, v67, 0x3fb8aa3b, v91
	v_fmamk_f32 v68, v68, 0x3fb8aa3b, v91
	v_fmamk_f32 v69, v69, 0x3fb8aa3b, v91
	v_exp_f32_e32 v66, v66
	v_exp_f32_e32 v67, v67
	v_exp_f32_e32 v68, v68
	v_exp_f32_e32 v69, v69
	v_fmamk_f32 v70, v70, 0x3fb8aa3b, v91
	v_fmamk_f32 v71, v71, 0x3fb8aa3b, v91
	v_fmamk_f32 v72, v72, 0x3fb8aa3b, v91
	v_fmamk_f32 v73, v73, 0x3fb8aa3b, v91
	v_exp_f32_e32 v70, v70
	v_exp_f32_e32 v71, v71
	v_exp_f32_e32 v72, v72
	v_exp_f32_e32 v73, v73
	v_fmamk_f32 v74, v74, 0x3fb8aa3b, v91
	v_fmamk_f32 v75, v75, 0x3fb8aa3b, v91
	v_fmamk_f32 v76, v76, 0x3fb8aa3b, v91
	v_fmamk_f32 v77, v77, 0x3fb8aa3b, v91
	v_exp_f32_e32 v74, v74
	v_exp_f32_e32 v75, v75
	v_exp_f32_e32 v76, v76
	v_exp_f32_e32 v77, v77
	s_nop 0
	v_add_f32_e32 v86, v62, v63
	v_add_f32_e32 v87, v64, v65
	v_add_f32_e32 v88, v66, v67
	v_add_f32_e32 v89, v68, v69
	v_add_f32_e32 v86, v86, v70
	v_add_f32_e32 v87, v87, v71
	v_add_f32_e32 v88, v88, v72
	v_add_f32_e32 v89, v89, v73
	v_add_f32_e32 v86, v86, v74
	v_add_f32_e32 v87, v87, v75
	v_add_f32_e32 v88, v88, v76
	v_add_f32_e32 v89, v89, v77
	v_add_f32_e32 v86, v86, v87
	v_add_f32_e32 v88, v88, v89
	v_add_f32_e32 v86, v86, v88
	v_cvt_pk_bf16_f32 v78, v62, v63
	v_cvt_pk_bf16_f32 v79, v64, v65
	v_cvt_pk_bf16_f32 v80, v66, v67
	v_cvt_pk_bf16_f32 v81, v68, v69
	v_cvt_pk_bf16_f32 v82, v70, v71
	v_cvt_pk_bf16_f32 v83, v72, v73
	v_cvt_pk_bf16_f32 v84, v74, v75
	v_cvt_pk_bf16_f32 v85, v76, v77
	v_mov_b32_e32 v87, v86
	s_nop 1
	v_permlane16_swap_b32_e32 v86, v87
	v_add_f32_e32 v86, v86, v87
	v_mov_b32_e32 v87, v86
	s_nop 1
	v_permlane32_swap_b32_e32 v86, v87
	v_add_f32_e32 v86, v86, v87
	v_fma_f32 v138, v138, v90, v86
	v_cmp_neq_f32_e64 s[0:1], 1.0, v90
	s_cmp_eq_u64 s[0:1], 0
	s_cbranch_scc1 .Lcm_nosc_6
	v_pk_mul_f32 v[30:31], v[30:31], v[90:91] op_sel_hi:[1,0]
	v_pk_mul_f32 v[32:33], v[32:33], v[90:91] op_sel_hi:[1,0]
	v_pk_mul_f32 v[34:35], v[34:35], v[90:91] op_sel_hi:[1,0]
	v_pk_mul_f32 v[36:37], v[36:37], v[90:91] op_sel_hi:[1,0]
	v_pk_mul_f32 v[38:39], v[38:39], v[90:91] op_sel_hi:[1,0]
	v_pk_mul_f32 v[40:41], v[40:41], v[90:91] op_sel_hi:[1,0]
	v_pk_mul_f32 v[42:43], v[42:43], v[90:91] op_sel_hi:[1,0]
	v_pk_mul_f32 v[44:45], v[44:45], v[90:91] op_sel_hi:[1,0]
	v_pk_mul_f32 v[46:47], v[46:47], v[90:91] op_sel_hi:[1,0]
	v_pk_mul_f32 v[48:49], v[48:49], v[90:91] op_sel_hi:[1,0]
	v_pk_mul_f32 v[50:51], v[50:51], v[90:91] op_sel_hi:[1,0]
	v_pk_mul_f32 v[52:53], v[52:53], v[90:91] op_sel_hi:[1,0]
	v_pk_mul_f32 v[54:55], v[54:55], v[90:91] op_sel_hi:[1,0]
	v_pk_mul_f32 v[56:57], v[56:57], v[90:91] op_sel_hi:[1,0]
	v_pk_mul_f32 v[58:59], v[58:59], v[90:91] op_sel_hi:[1,0]
	v_pk_mul_f32 v[60:61], v[60:61], v[90:91] op_sel_hi:[1,0]

; #define LAS __attribute__((address_space(3)))
; __device__ __forceinline__ unsigned cvt_pk_bf16(float lo, float hi) { unsigned r; asm("v_cvt_pk_bf16_f32 %0, %1, %2" : "=v"(r) : "v"(lo), "v"(hi)); return r; }
; template <int D, class SF>
; __device__ __forceinline__ void attn_step(const bf16x8 (&qf)[D / 32], const LAS bf16_t* Ks, const LAS bf16_t* Vt, f32x4 (&o)[D / 16], float& m, float& lsum, float& alpha_out, bf16x8& pf0_out, bf16x8& pf1_out, const int lane, SF sf) {
;     ...
;     for (int ks = 0; ks < D / 32; ++ks) {
; #pragma unroll
;         for (int t = 0; t < 4; ++t) { const bf16x8 kf = *(const LAS bf16x8*)(Ks + (16 * t + c) * KSTR + ks * 32 + 8 * i); s[t] = mfma16(kf, qf[ks], s[t]); }
;     }
;     float v[16];
; #pragma unroll
;     for (int t = 0; t < 4; ++t)
; #pragma unroll
;         for (int r = 0; r < 4; ++r) v[4 * t + r] = sf(16 * t + 4 * i + r, s[t][r]);
;     float mx = fmaxf(fmaxf(fmaxf(v[0], v[1]), fmaxf(v[2], v[3])), fmaxf(fmaxf(v[4], v[5]), fmaxf(v[6], v[7])));
;     mx = fmaxf(mx, fmaxf(fmaxf(fmaxf(v[8], v[9]), fmaxf(v[10], v[11])), fmaxf(fmaxf(v[12], v[13]), fmaxf(v[14], v[15]))));
;     mx = rows_max(mx);
;     const float mnew = fmaxf(m, mx);
;     const float mc = fmaxf(mnew, -1e20f);
;     const float alpha = __builtin_amdgcn_exp2f(fmaxf(m, -1e20f) - mc);
;     float p[16], rs = 0.f;
; #pragma unroll
;     for (int r = 0; r < 16; ++r) { p[r] = __builtin_amdgcn_exp2f(v[r] - mc); rs += p[r]; }
;     rs = rows_sum(rs);
;     lsum = lsum * alpha + rs; m = mnew;
;     union { u32x4 u; bf16x8 b; } pk0, pk1;
;     pk0.u.x = cvt_pk_bf16(p[0], p[1]); pk0.u.y = cvt_pk_bf16(p[2], p[3]); pk0.u.z = cvt_pk_bf16(p[4], p[5]); pk0.u.w = cvt_pk_bf16(p[6], p[7]);
;     pk1.u.x = cvt_pk_bf16(p[8], p[9]); pk1.u.y = cvt_pk_bf16(p[10], p[11]); pk1.u.z = cvt_pk_bf16(p[12], p[13]); pk1.u.w = cvt_pk_bf16(p[14], p[15]);
;     if (__builtin_amdgcn_ballot_w64(alpha != 1.0f) != 0ull) {
; #pragma unroll
;         for (int dt = 0; dt < D / 16; ++dt) o[dt] *= alpha;
; __device__ __forceinline__ void nsa_unit(LAS unsigned char* lds, const Ctx& P, int l, int b, int hkv, int tb) {
;     ...
;                 oi[kt] = mfma16(ovA[0], pf, oi[kt]); oi[kt] = mfma16(ovA[1], pf1, oi[kt]);
;                 if (kt + 1 < 4) { oi[kt + 1 < 4 ? kt + 1 : 3] = mfma16(ovB[0], pf, oi[kt + 1 < 4 ? kt + 1 : 3]); oi[kt + 1 < 4 ? kt + 1 : 3] = mfma16(ovB[1], pf1, oi[kt + 1 < 4 ? kt + 1 : 3]); }
.Lcm_nob_7:
	v_mfma_f32_16x16x32_bf16 v[46:49], v[170:173], v[82:85], v[46:49]
	ds_read_b128 v[198:201], v192 offset:16384
	ds_read_b128 v[206:209], v192 offset:18944
	ds_read_b128 v[202:205], v192 offset:16448
	ds_read_b128 v[210:213], v192 offset:19008
	ds_read_b128 v[214:217], v192 offset:21504
	ds_read_b128 v[222:225], v192 offset:24064
	ds_read_b128 v[218:221], v192 offset:21568
	ds_read_b128 v[226:229], v192 offset:24128
	s_waitcnt lgkmcnt(6)
	v_mfma_f32_16x16x32_bf16 v[62:65], v[198:201], v[10:13], 0
	v_mfma_f32_16x16x32_bf16 v[66:69], v[206:209], v[10:13], 0
	s_waitcnt lgkmcnt(4)
	v_mfma_f32_16x16x32_bf16 v[62:65], v[202:205], v[14:17], v[62:65]
	v_mfma_f32_16x16x32_bf16 v[66:69], v[210:213], v[14:17], v[66:69]
	s_waitcnt lgkmcnt(2)
	v_mfma_f32_16x16x32_bf16 v[70:73], v[214:217], v[10:13], 0
	v_mfma_f32_16x16x32_bf16 v[74:77], v[222:225], v[10:13], 0
	s_waitcnt lgkmcnt(0)
	v_mfma_f32_16x16x32_bf16 v[70:73], v[218:221], v[14:17], v[70:73]
	v_mfma_f32_16x16x32_bf16 v[74:77], v[226:229], v[14:17], v[74:77]
	ds_read_b64_tr_b16 v[198:199], v193 offset:26624
	ds_read_b64_tr_b16 v[200:201], v193 offset:29184
	ds_read_b64_tr_b16 v[202:203], v193 offset:31744
	ds_read_b64_tr_b16 v[204:205], v193 offset:34304
	ds_read_b64_tr_b16 v[206:207], v193 offset:26656
	ds_read_b64_tr_b16 v[208:209], v193 offset:29216
	ds_read_b64_tr_b16 v[210:211], v193 offset:31776
	ds_read_b64_tr_b16 v[212:213], v193 offset:34336
	ds_read_b64_tr_b16 v[214:215], v193 offset:26688
	ds_read_b64_tr_b16 v[216:217], v193 offset:29248
	ds_read_b64_tr_b16 v[218:219], v193 offset:31808
	ds_read_b64_tr_b16 v[220:221], v193 offset:34368
	ds_read_b64_tr_b16 v[222:223], v193 offset:26720
	ds_read_b64_tr_b16 v[224:225], v193 offset:29280
	ds_read_b64_tr_b16 v[226:227], v193 offset:31840
	ds_read_b64_tr_b16 v[228:229], v193 offset:34400
	v_max3_f32 v86, v62, v63, v64
	v_max3_f32 v87, v65, v66, v67
	v_max3_f32 v88, v68, v69, v70
	v_max3_f32 v89, v71, v72, v73
	v_max3_f32 v91, v74, v75, v76
	v_max3_f32 v86, v86, v87, v77
	v_max3_f32 v88, v88, v89, v91
	v_max_f32_e32 v86, v86, v88
	v_mov_b32_e32 v87, v86
	s_nop 1
	v_permlane16_swap_b32_e32 v86, v87
	v_max_f32_e32 v86, v86, v87
	v_mov_b32_e32 v87, v86
	s_nop 1
	v_permlane32_swap_b32_e32 v86, v87
	v_max_f32_e32 v86, v86, v87
	v_fmamk_f32 v86, v86, 0x3fb8aa3b, v165
	v_cndmask_b32_e64 v86, v243, v86, s[24:25]
	v_max_f32_e32 v88, v195, v86
	v_max_f32_e32 v90, 0xe0ad78ec, v195
	v_max_f32_e32 v89, 0xe0ad78ec, v88
	v_sub_f32_e32 v90, v90, v89
	v_mov_b32_e32 v195, v88
	v_exp_f32_e32 v90, v90
	v_sub_f32_e32 v91, v165, v89
	v_cndmask_b32_e64 v91, v243, v91, s[24:25]
	v_fmamk_f32 v62, v62, 0x3fb8aa3b, v91
	v_fmamk_f32 v63, v63, 0x3fb8aa3b, v91
	v_fmamk_f32 v64, v64, 0x3fb8aa3b, v91
	v_fmamk_f32 v65, v65, 0x3fb8aa3b, v91
	v_exp_f32_e32 v62, v62
	v_exp_f32_e32 v63, v63
	v_exp_f32_e32 v64, v64
	v_exp_f32_e32 v65, v65
	v_fmamk_f32 v66, v66, 0x3fb8aa3b, v91
	v_fmamk_f32 v67, v67, 0x3fb8aa3b, v91
	v_fmamk_f32 v68, v68, 0x3fb8aa3b, v91
	v_fmamk_f32 v69, v69, 0x3fb8aa3b, v91
	v_exp_f32_e32 v66, v66
	v_exp_f32_e32 v67, v67
	v_exp_f32_e32 v68, v68
	v_exp_f32_e32 v69, v69
	v_fmamk_f32 v70, v70, 0x3fb8aa3b, v91
	v_fmamk_f32 v71, v71, 0x3fb8aa3b, v91
	v_fmamk_f32 v72, v72, 0x3fb8aa3b, v91
	v_fmamk_f32 v73, v73, 0x3fb8aa3b, v91
	v_exp_f32_e32 v70, v70
	v_exp_f32_e32 v71, v71
	v_exp_f32_e32 v72, v72
	v_exp_f32_e32 v73, v73
	v_fmamk_f32 v74, v74, 0x3fb8aa3b, v91
	v_fmamk_f32 v75, v75, 0x3fb8aa3b, v91
	v_fmamk_f32 v76, v76, 0x3fb8aa3b, v91
	v_fmamk_f32 v77, v77, 0x3fb8aa3b, v91
	v_exp_f32_e32 v74, v74
	v_exp_f32_e32 v75, v75
	v_exp_f32_e32 v76, v76
	v_exp_f32_e32 v77, v77
	s_nop 0
	v_add_f32_e32 v86, v62, v63
	v_add_f32_e32 v87, v64, v65
	v_add_f32_e32 v88, v66, v67
	v_add_f32_e32 v89, v68, v69
	v_add_f32_e32 v86, v86, v70
	v_add_f32_e32 v87, v87, v71
	v_add_f32_e32 v88, v88, v72
	v_add_f32_e32 v89, v89, v73
	v_add_f32_e32 v86, v86, v74
	v_add_f32_e32 v87, v87, v75
	v_add_f32_e32 v88, v88, v76
	v_add_f32_e32 v89, v89, v77
	v_add_f32_e32 v86, v86, v87
	v_add_f32_e32 v88, v88, v89
	v_add_f32_e32 v86, v86, v88
	v_cvt_pk_bf16_f32 v78, v62, v63
	v_cvt_pk_bf16_f32 v79, v64, v65
	v_cvt_pk_bf16_f32 v80, v66, v67
	v_cvt_pk_bf16_f32 v81, v68, v69
	v_cvt_pk_bf16_f32 v82, v70, v71
	v_cvt_pk_bf16_f32 v83, v72, v73
	v_cvt_pk_bf16_f32 v84, v74, v75
	v_cvt_pk_bf16_f32 v85, v76, v77
	v_mov_b32_e32 v87, v86
	s_nop 1
	v_permlane16_swap_b32_e32 v86, v87
	v_add_f32_e32 v86, v86, v87
	v_mov_b32_e32 v87, v86
	s_nop 1
	v_permlane32_swap_b32_e32 v86, v87
	v_add_f32_e32 v86, v86, v87
	v_fma_f32 v196, v196, v90, v86
	v_cmp_neq_f32_e64 s[0:1], 1.0, v90
	s_cmp_eq_u64 s[0:1], 0
	s_cbranch_scc1 .Lcm_nosc_8
	v_pk_mul_f32 v[174:175], v[174:175], v[90:91] op_sel_hi:[1,0]
	v_pk_mul_f32 v[176:177], v[176:177], v[90:91] op_sel_hi:[1,0]
	v_pk_mul_f32 v[178:179], v[178:179], v[90:91] op_sel_hi:[1,0]
	v_pk_mul_f32 v[180:181], v[180:181], v[90:91] op_sel_hi:[1,0]
	v_pk_mul_f32 v[182:183], v[182:183], v[90:91] op_sel_hi:[1,0]
	v_pk_mul_f32 v[184:185], v[184:185], v[90:91] op_sel_hi:[1,0]
	v_pk_mul_f32 v[186:187], v[186:187], v[90:91] op_sel_hi:[1,0]
	v_pk_mul_f32 v[188:189], v[188:189], v[90:91] op_sel_hi:[1,0]
	v_pk_mul_f32 v[18:19], v[18:19], v[90:91] op_sel_hi:[1,0]
	v_pk_mul_f32 v[20:21], v[20:21], v[90:91] op_sel_hi:[1,0]
	v_pk_mul_f32 v[22:23], v[22:23], v[90:91] op_sel_hi:[1,0]
	v_pk_mul_f32 v[24:25], v[24:25], v[90:91] op_sel_hi:[1,0]
	v_pk_mul_f32 v[26:27], v[26:27], v[90:91] op_sel_hi:[1,0]
	v_pk_mul_f32 v[28:29], v[28:29], v[90:91] op_sel_hi:[1,0]
	v_pk_mul_f32 v[104:105], v[104:105], v[90:91] op_sel_hi:[1,0]
	v_pk_mul_f32 v[106:107], v[106:107], v[90:91] op_sel_hi:[1,0]

; __device__ __forceinline__ f32x4 mfma16(bf16x8 a, bf16x8 b, f32x4 c) { return __builtin_amdgcn_mfma_f32_16x16x32_bf16(a, b, c, 0, 0, 0); }
; __device__ __forceinline__ void nsa_unit(LAS unsigned char* lds, const Ctx& P, int l, int b, int hkv, int tb) {
;     ...
;                 oi[kt] = mfma16(ovA[0], pf, oi[kt]); oi[kt] = mfma16(ovA[1], pf1, oi[kt]);
;                 if (kt + 1 < 4) { oi[kt + 1 < 4 ? kt + 1 : 3] = mfma16(ovB[0], pf, oi[kt + 1 < 4 ? kt + 1 : 3]); oi[kt + 1 < 4 ? kt + 1 : 3] = mfma16(ovB[1], pf1, oi[kt + 1 < 4 ? kt + 1 : 3]); }
.Lcm_nob_9:
	v_mfma_f32_16x16x32_bf16 v[18:21], v[170:173], v[82:85], v[18:21]
	s_branch .Lcm_join_5

; __device__ __forceinline__ f32x4 mfma16(bf16x8 a, bf16x8 b, f32x4 c) { return __builtin_amdgcn_mfma_f32_16x16x32_bf16(a, b, c, 0, 0, 0); }
; __device__ __forceinline__ void nsa_unit(LAS unsigned char* lds, const Ctx& P, int l, int b, int hkv, int tb) {
;     ...
;         for (int pr = 0; pr < 2; ++pr) if (2 * pr < ntile) {
;     ...
; #pragma unroll
;                 for (int jt = 0; jt < 4; ++jt) oi[jt] *= alpha;
;                 oi[kt] = mfma16(ovA[0], pf, oi[kt]); oi[kt] = mfma16(ovA[1], pf1, oi[kt]);
;                 if (kt + 1 < 4) { oi[kt + 1 < 4 ? kt + 1 : 3] = mfma16(ovB[0], pf, oi[kt + 1 < 4 ? kt + 1 : 3]); oi[kt + 1 < 4 ? kt + 1 : 3] = mfma16(ovB[1], pf1, oi[kt + 1 < 4 ? kt + 1 : 3]); }
;             }
.Lcm_join_5:
	s_nop 7
	v_swap_b32 v46, v50
	v_swap_b32 v50, v54
	v_swap_b32 v54, v58
	v_swap_b32 v47, v51
	v_swap_b32 v51, v55
	v_swap_b32 v55, v59
	v_swap_b32 v48, v52
	v_swap_b32 v52, v56
	v_swap_b32 v56, v60
	v_swap_b32 v49, v53
	v_swap_b32 v53, v57
	v_swap_b32 v57, v61
	v_swap_b32 v18, v22
	v_swap_b32 v22, v26
	v_swap_b32 v26, v104
	v_swap_b32 v19, v23
	v_swap_b32 v23, v27
	v_swap_b32 v27, v105
	v_swap_b32 v20, v24
	v_swap_b32 v24, v28
	v_swap_b32 v28, v106
	v_swap_b32 v21, v25
	v_swap_b32 v25, v29
	v_swap_b32 v29, v107
	v_add_u32_e32 v192, 0x5000, v192
	v_add_u32_e32 v193, 0x5000, v193
	s_add_i32 s4, s4, 1
	s_addk_i32 s5, 0x400
	s_cmp_lt_u32 s4, s26
	s_cbranch_scc1 .Lcm_top_3
